# P7 epilogue: removed 92 dead zero-init v_mov (left over from the LDS halo reads replaced by DPP)
# speedup vs baseline: 1.0000x; 1.0000x over previous
; #define LAS __attribute__((address_space(3)))
; __device__ __forceinline__ u32x2 pack4(f32x4 v) { u32x2 r; r.x = cvt_pk(v[0], v[1]); r.y = cvt_pk(v[2], v[3]); return r; }
; __device__ __forceinline__ float dpp_shr1(float v) { return __builtin_bit_cast(float, __builtin_amdgcn_update_dpp(0, __builtin_bit_cast(int, v), 0x111, 0xf, 0xf, true)); }
; __device__ __forceinline__ float dpp_shr2(float v) { return __builtin_bit_cast(float, __builtin_amdgcn_update_dpp(0, __builtin_bit_cast(int, v), 0x112, 0xf, 0xf, true)); }
; #define FOR_AI_M _Pragma("unroll") for (int ai = 0; ai < 2; ++ai) _Pragma("unroll") for (int m = 0; m < 4; ++m)
;     __device__ __forceinline__ void operator()(EPI_ARGS) const {
;     ...
;         FOR_AI_M {
;             const int R = ai * 128 + wr * 64 + m * 16 + fr; const int rb = ai * 8 + wr * 4 + m;
;             u32x4 ow;
;             const bool valid = gather ? ((R & 3) >= 2) : (R >= 2);
;             const int orow = gather ? (256 * (R >> 2) + 252 + (R & 3)) : (256 * u.pm + R - 2);
; #pragma unroll
;             for (int n = 0; n < 2; ++n) {
;                 const int cl = wc * 32 + 8 * fq + 4 * n;
;                 f32x4 hA = (f32x4){0.f, 0.f, 0.f, 0.f}, hB = (f32x4){0.f, 0.f, 0.f, 0.f};
;                 if (fr < 2 && rb > 0) { hA = *(const LAS f32x4*)(halo + (((rb - 1) * 2 + fr) * 128 + cl)); if (fr == 0) hB = *(const LAS f32x4*)(halo + (((rb - 1) * 2 + 1) * 128 + cl)); }
;                 const f32x4 g0 = acc[ai][0][m][n], vv = acc[ai][1][m][n];
;                 f32x4 d1, d2;
; #pragma unroll
;                 for (int e = 0; e < 4; ++e) { d1[e] = dpp_shr1(g0[e]); d2[e] = dpp_shr2(g0[e]); }
;                 const f32x4 g1 = d1 + hB, g2 = d2 + hA;
;                 const f32x4 cv = W0[n] * g2 + (W1[n] * g1 + (W2[n] * g0 + BB[n]));
;                 const f32x4 tt = cv * -1.4426950408889634f; f32x4 den;
; #pragma unroll
;                 for (int e = 0; e < 4; ++e) den[e] = __builtin_amdgcn_exp2f(tt[e]);
;                 den = den + 1.0f; f32x4 rc;
; #pragma unroll
;                 for (int e = 0; e < 4; ++e) rc[e] = __builtin_amdgcn_rcpf(den[e]);
;                 const f32x4 o = (cv * rc) * vv;
;                 const u32x2 pk = pack4(o); if (n == 0) { ow.x = pk.x; ow.y = pk.y; } else { ow.z = pk.x; ow.w = pk.y; }
;             }
;             if (valid) *(u32x4*)(ACT + ((size_t)orow * DFF + u.pn * 128 + wc * 32 + 8 * fq)) = ow;
.LBB0_1117:
	s_or_b64 exec, exec, s[8:9]
	s_cmp_gt_i32 s81, -1
	s_cselect_b64 s[8:9], -1, 0
	s_and_b64 s[12:13], s[46:47], s[8:9]
	v_lshl_add_u32 v210, v187, 2, v199
.LBB0_1121:
	s_waitcnt lgkmcnt(0)
	v_mov_b32_dpp v168, v66 row_ror:1 row_mask:0xf bank_mask:0xf
	v_mov_b32_dpp v169, v67 row_ror:1 row_mask:0xf bank_mask:0xf
	s_nop 0
	v_mov_b32_dpp v168, v122 row_shr:1 row_mask:0xf bank_mask:0xf
	v_mov_b32_dpp v169, v123 row_shr:1 row_mask:0xf bank_mask:0xf
	v_mov_b32_dpp v166, v64 row_ror:1 row_mask:0xf bank_mask:0xf
	v_mov_b32_dpp v167, v65 row_ror:1 row_mask:0xf bank_mask:0xf
	s_nop 0
	v_mov_b32_dpp v166, v120 row_shr:1 row_mask:0xf bank_mask:0xf
	v_mov_b32_dpp v167, v121 row_shr:1 row_mask:0xf bank_mask:0xf
	v_mov_b32_dpp v162, v64 row_ror:2 row_mask:0xf bank_mask:0xf
	v_mov_b32_dpp v163, v65 row_ror:2 row_mask:0xf bank_mask:0xf
	s_nop 0
	v_mov_b32_dpp v162, v120 row_shr:2 row_mask:0xf bank_mask:0xf
	v_mov_b32_dpp v163, v121 row_shr:2 row_mask:0xf bank_mask:0xf
	v_pk_fma_f32 v[208:209], v[154:155], v[122:123], v[158:159]
	v_pk_fma_f32 v[224:225], v[152:153], v[120:121], v[156:157]
	v_mov_b32_dpp v164, v66 row_ror:2 row_mask:0xf bank_mask:0xf
	v_mov_b32_dpp v165, v67 row_ror:2 row_mask:0xf bank_mask:0xf
	s_nop 0
	v_mov_b32_dpp v164, v122 row_shr:2 row_mask:0xf bank_mask:0xf
	v_mov_b32_dpp v165, v123 row_shr:2 row_mask:0xf bank_mask:0xf
	v_pk_fma_f32 v[166:167], v[148:149], v[166:167], v[224:225]
	v_pk_fma_f32 v[168:169], v[150:151], v[168:169], v[208:209]
	v_pk_fma_f32 v[162:163], v[144:145], v[162:163], v[166:167]
	v_pk_fma_f32 v[164:165], v[146:147], v[164:165], v[168:169]
	v_mul_f32_e32 v161, 0xbfb8aa3b, v162
	v_mul_f32_e32 v167, 0xbfb8aa3b, v164
	v_exp_f32_e32 v166, v161
	v_mul_f32_e32 v161, 0xbfb8aa3b, v163
	v_exp_f32_e32 v168, v167
	v_mul_f32_e32 v167, 0xbfb8aa3b, v165
	v_exp_f32_e32 v169, v167
	v_exp_f32_e32 v167, v161
	v_mov_b32_e32 v207, v206
	v_mov_b32_e32 v208, v206
	v_pk_add_f32 v[168:169], v[168:169], 1.0 op_sel_hi:[1,0]
	v_pk_add_f32 v[166:167], v[166:167], 1.0 op_sel_hi:[1,0]
	v_rcp_f32_e32 v168, v168
	v_rcp_f32_e32 v166, v166
	v_rcp_f32_e32 v167, v167
	v_rcp_f32_e32 v169, v169
	v_mov_b32_e32 v209, v206
	v_pk_mul_f32 v[90:91], v[90:91], v[208:209]
	v_pk_mul_f32 v[88:89], v[88:89], v[206:207]
	v_pk_mul_f32 v[162:163], v[162:163], v[166:167]
	v_pk_mul_f32 v[164:165], v[164:165], v[168:169]
	v_pk_mul_f32 v[162:163], v[88:89], v[162:163]
	v_pk_mul_f32 v[166:167], v[90:91], v[164:165]
	v_cvt_pk_bf16_f32 v164, v162, v163
	v_cvt_pk_bf16_f32 v165, v166, v167

; #define LAS __attribute__((address_space(3)))
; __device__ __forceinline__ u32x2 pack4(f32x4 v) { u32x2 r; r.x = cvt_pk(v[0], v[1]); r.y = cvt_pk(v[2], v[3]); return r; }
; __device__ __forceinline__ float dpp_shr1(float v) { return __builtin_bit_cast(float, __builtin_amdgcn_update_dpp(0, __builtin_bit_cast(int, v), 0x111, 0xf, 0xf, true)); }
; __device__ __forceinline__ float dpp_shr2(float v) { return __builtin_bit_cast(float, __builtin_amdgcn_update_dpp(0, __builtin_bit_cast(int, v), 0x112, 0xf, 0xf, true)); }
; #define FOR_AI_M _Pragma("unroll") for (int ai = 0; ai < 2; ++ai) _Pragma("unroll") for (int m = 0; m < 4; ++m)
;     __device__ __forceinline__ void operator()(EPI_ARGS) const {
;     ...
;         FOR_AI_M {
;             const int R = ai * 128 + wr * 64 + m * 16 + fr; const int rb = ai * 8 + wr * 4 + m;
;             u32x4 ow;
;             const bool valid = gather ? ((R & 3) >= 2) : (R >= 2);
;             const int orow = gather ? (256 * (R >> 2) + 252 + (R & 3)) : (256 * u.pm + R - 2);
; #pragma unroll
;             for (int n = 0; n < 2; ++n) {
;                 const int cl = wc * 32 + 8 * fq + 4 * n;
;                 f32x4 hA = (f32x4){0.f, 0.f, 0.f, 0.f}, hB = (f32x4){0.f, 0.f, 0.f, 0.f};
;                 if (fr < 2 && rb > 0) { hA = *(const LAS f32x4*)(halo + (((rb - 1) * 2 + fr) * 128 + cl)); if (fr == 0) hB = *(const LAS f32x4*)(halo + (((rb - 1) * 2 + 1) * 128 + cl)); }
;                 const f32x4 g0 = acc[ai][0][m][n], vv = acc[ai][1][m][n];
;                 f32x4 d1, d2;
; #pragma unroll
;                 for (int e = 0; e < 4; ++e) { d1[e] = dpp_shr1(g0[e]); d2[e] = dpp_shr2(g0[e]); }
;                 const f32x4 g1 = d1 + hB, g2 = d2 + hA;
;                 const f32x4 cv = W0[n] * g2 + (W1[n] * g1 + (W2[n] * g0 + BB[n]));
;                 const f32x4 tt = cv * -1.4426950408889634f; f32x4 den;
; #pragma unroll
;                 for (int e = 0; e < 4; ++e) den[e] = __builtin_amdgcn_exp2f(tt[e]);
;                 den = den + 1.0f; f32x4 rc;
; #pragma unroll
;                 for (int e = 0; e < 4; ++e) rc[e] = __builtin_amdgcn_rcpf(den[e]);
;                 const f32x4 o = (cv * rc) * vv;
;                 const u32x2 pk = pack4(o); if (n == 0) { ow.x = pk.x; ow.y = pk.y; } else { ow.z = pk.x; ow.w = pk.y; }
;             }
;             if (valid) *(u32x4*)(ACT + ((size_t)orow * DFF + u.pn * 128 + wc * 32 + 8 * fq)) = ow;
.LBB0_1131:
	s_waitcnt lgkmcnt(0)
	v_mov_b32_dpp v168, v122 row_ror:1 row_mask:0xf bank_mask:0xf
	v_mov_b32_dpp v169, v123 row_ror:1 row_mask:0xf bank_mask:0xf
	s_nop 0
	v_mov_b32_dpp v168, v114 row_shr:1 row_mask:0xf bank_mask:0xf
	v_mov_b32_dpp v169, v115 row_shr:1 row_mask:0xf bank_mask:0xf
	v_mov_b32_dpp v166, v120 row_ror:1 row_mask:0xf bank_mask:0xf
	v_mov_b32_dpp v167, v121 row_ror:1 row_mask:0xf bank_mask:0xf
	s_nop 0
	v_mov_b32_dpp v166, v112 row_shr:1 row_mask:0xf bank_mask:0xf
	v_mov_b32_dpp v167, v113 row_shr:1 row_mask:0xf bank_mask:0xf
	v_mov_b32_dpp v162, v120 row_ror:2 row_mask:0xf bank_mask:0xf
	v_mov_b32_dpp v163, v121 row_ror:2 row_mask:0xf bank_mask:0xf
	s_nop 0
	v_mov_b32_dpp v162, v112 row_shr:2 row_mask:0xf bank_mask:0xf
	v_mov_b32_dpp v163, v113 row_shr:2 row_mask:0xf bank_mask:0xf
	v_pk_fma_f32 v[206:207], v[154:155], v[114:115], v[158:159]
	v_pk_fma_f32 v[224:225], v[152:153], v[112:113], v[156:157]
	v_mov_b32_dpp v164, v122 row_ror:2 row_mask:0xf bank_mask:0xf
	v_mov_b32_dpp v165, v123 row_ror:2 row_mask:0xf bank_mask:0xf
	s_nop 0
	v_mov_b32_dpp v164, v114 row_shr:2 row_mask:0xf bank_mask:0xf
	v_mov_b32_dpp v165, v115 row_shr:2 row_mask:0xf bank_mask:0xf
	v_pk_fma_f32 v[166:167], v[148:149], v[166:167], v[224:225]
	v_pk_fma_f32 v[168:169], v[150:151], v[168:169], v[206:207]
	v_pk_fma_f32 v[162:163], v[144:145], v[162:163], v[166:167]
	v_pk_fma_f32 v[164:165], v[146:147], v[164:165], v[168:169]
	v_mul_f32_e32 v161, 0xbfb8aa3b, v162
	v_mul_f32_e32 v167, 0xbfb8aa3b, v164
	v_exp_f32_e32 v166, v161
	v_mul_f32_e32 v161, 0xbfb8aa3b, v163
	v_exp_f32_e32 v168, v167
	v_mul_f32_e32 v167, 0xbfb8aa3b, v165
	v_exp_f32_e32 v169, v167
	v_exp_f32_e32 v167, v161
	v_mov_b32_e32 v205, v204
	v_mov_b32_e32 v206, v204
	v_pk_add_f32 v[168:169], v[168:169], 1.0 op_sel_hi:[1,0]
	v_pk_add_f32 v[166:167], v[166:167], 1.0 op_sel_hi:[1,0]
	v_rcp_f32_e32 v168, v168
	v_rcp_f32_e32 v166, v166
	v_rcp_f32_e32 v167, v167
	v_rcp_f32_e32 v169, v169
	v_mov_b32_e32 v207, v204
	v_pk_mul_f32 v[82:83], v[82:83], v[206:207]
	v_pk_mul_f32 v[80:81], v[80:81], v[204:205]
	v_pk_mul_f32 v[162:163], v[162:163], v[166:167]
	v_pk_mul_f32 v[164:165], v[164:165], v[168:169]
	v_pk_mul_f32 v[162:163], v[80:81], v[162:163]
	v_pk_mul_f32 v[166:167], v[82:83], v[164:165]
	v_cvt_pk_bf16_f32 v164, v162, v163
	v_cvt_pk_bf16_f32 v165, v166, v167

; #define LAS __attribute__((address_space(3)))
; __device__ __forceinline__ u32x2 pack4(f32x4 v) { u32x2 r; r.x = cvt_pk(v[0], v[1]); r.y = cvt_pk(v[2], v[3]); return r; }
; __device__ __forceinline__ float dpp_shr1(float v) { return __builtin_bit_cast(float, __builtin_amdgcn_update_dpp(0, __builtin_bit_cast(int, v), 0x111, 0xf, 0xf, true)); }
; __device__ __forceinline__ float dpp_shr2(float v) { return __builtin_bit_cast(float, __builtin_amdgcn_update_dpp(0, __builtin_bit_cast(int, v), 0x112, 0xf, 0xf, true)); }
; #define FOR_AI_M _Pragma("unroll") for (int ai = 0; ai < 2; ++ai) _Pragma("unroll") for (int m = 0; m < 4; ++m)
;     __device__ __forceinline__ void operator()(EPI_ARGS) const {
;     ...
;         FOR_AI_M {
;             const int R = ai * 128 + wr * 64 + m * 16 + fr; const int rb = ai * 8 + wr * 4 + m;
;             u32x4 ow;
;             const bool valid = gather ? ((R & 3) >= 2) : (R >= 2);
;             const int orow = gather ? (256 * (R >> 2) + 252 + (R & 3)) : (256 * u.pm + R - 2);
; #pragma unroll
;             for (int n = 0; n < 2; ++n) {
;                 const int cl = wc * 32 + 8 * fq + 4 * n;
;                 f32x4 hA = (f32x4){0.f, 0.f, 0.f, 0.f}, hB = (f32x4){0.f, 0.f, 0.f, 0.f};
;                 if (fr < 2 && rb > 0) { hA = *(const LAS f32x4*)(halo + (((rb - 1) * 2 + fr) * 128 + cl)); if (fr == 0) hB = *(const LAS f32x4*)(halo + (((rb - 1) * 2 + 1) * 128 + cl)); }
;                 const f32x4 g0 = acc[ai][0][m][n], vv = acc[ai][1][m][n];
;                 f32x4 d1, d2;
; #pragma unroll
;                 for (int e = 0; e < 4; ++e) { d1[e] = dpp_shr1(g0[e]); d2[e] = dpp_shr2(g0[e]); }
;                 const f32x4 g1 = d1 + hB, g2 = d2 + hA;
;                 const f32x4 cv = W0[n] * g2 + (W1[n] * g1 + (W2[n] * g0 + BB[n]));
;                 const f32x4 tt = cv * -1.4426950408889634f; f32x4 den;
; #pragma unroll
;                 for (int e = 0; e < 4; ++e) den[e] = __builtin_amdgcn_exp2f(tt[e]);
;                 den = den + 1.0f; f32x4 rc;
; #pragma unroll
;                 for (int e = 0; e < 4; ++e) rc[e] = __builtin_amdgcn_rcpf(den[e]);
;                 const f32x4 o = (cv * rc) * vv;
;                 const u32x2 pk = pack4(o); if (n == 0) { ow.x = pk.x; ow.y = pk.y; } else { ow.z = pk.x; ow.w = pk.y; }
;             }
;             if (valid) *(u32x4*)(ACT + ((size_t)orow * DFF + u.pn * 128 + wc * 32 + 8 * fq)) = ow;
.LBB0_1141:
	s_waitcnt lgkmcnt(0)
	v_mov_b32_dpp v168, v114 row_ror:1 row_mask:0xf bank_mask:0xf
	v_mov_b32_dpp v169, v115 row_ror:1 row_mask:0xf bank_mask:0xf
	s_nop 0
	v_mov_b32_dpp v168, v106 row_shr:1 row_mask:0xf bank_mask:0xf
	v_mov_b32_dpp v169, v107 row_shr:1 row_mask:0xf bank_mask:0xf
	v_mov_b32_dpp v166, v112 row_ror:1 row_mask:0xf bank_mask:0xf
	v_mov_b32_dpp v167, v113 row_ror:1 row_mask:0xf bank_mask:0xf
	s_nop 0
	v_mov_b32_dpp v166, v104 row_shr:1 row_mask:0xf bank_mask:0xf
	v_mov_b32_dpp v167, v105 row_shr:1 row_mask:0xf bank_mask:0xf
	v_mov_b32_dpp v162, v112 row_ror:2 row_mask:0xf bank_mask:0xf
	v_mov_b32_dpp v163, v113 row_ror:2 row_mask:0xf bank_mask:0xf
	s_nop 0
	v_mov_b32_dpp v162, v104 row_shr:2 row_mask:0xf bank_mask:0xf
	v_mov_b32_dpp v163, v105 row_shr:2 row_mask:0xf bank_mask:0xf
	v_pk_fma_f32 v[204:205], v[154:155], v[106:107], v[158:159]
	v_pk_fma_f32 v[206:207], v[152:153], v[104:105], v[156:157]
	v_mov_b32_dpp v164, v114 row_ror:2 row_mask:0xf bank_mask:0xf
	v_mov_b32_dpp v165, v115 row_ror:2 row_mask:0xf bank_mask:0xf
	s_nop 0
	v_mov_b32_dpp v164, v106 row_shr:2 row_mask:0xf bank_mask:0xf
	v_mov_b32_dpp v165, v107 row_shr:2 row_mask:0xf bank_mask:0xf
	v_pk_fma_f32 v[166:167], v[148:149], v[166:167], v[206:207]
	v_pk_fma_f32 v[168:169], v[150:151], v[168:169], v[204:205]
	v_pk_fma_f32 v[162:163], v[144:145], v[162:163], v[166:167]
	v_pk_fma_f32 v[164:165], v[146:147], v[164:165], v[168:169]
	v_mul_f32_e32 v161, 0xbfb8aa3b, v162
	v_mul_f32_e32 v167, 0xbfb8aa3b, v164
	v_exp_f32_e32 v166, v161
	v_mul_f32_e32 v161, 0xbfb8aa3b, v163
	v_exp_f32_e32 v168, v167
	v_mul_f32_e32 v167, 0xbfb8aa3b, v165
	v_exp_f32_e32 v169, v167
	v_exp_f32_e32 v167, v161
	v_mov_b32_e32 v203, v202
	v_mov_b32_e32 v204, v202
	v_pk_add_f32 v[168:169], v[168:169], 1.0 op_sel_hi:[1,0]
	v_pk_add_f32 v[166:167], v[166:167], 1.0 op_sel_hi:[1,0]
	v_rcp_f32_e32 v168, v168
	v_rcp_f32_e32 v166, v166
	v_rcp_f32_e32 v167, v167
	v_rcp_f32_e32 v169, v169
	v_mov_b32_e32 v205, v202
	v_pk_mul_f32 v[74:75], v[74:75], v[204:205]
	v_pk_mul_f32 v[72:73], v[72:73], v[202:203]
	v_pk_mul_f32 v[162:163], v[162:163], v[166:167]
	v_pk_mul_f32 v[164:165], v[164:165], v[168:169]
	v_pk_mul_f32 v[162:163], v[72:73], v[162:163]
	v_pk_mul_f32 v[166:167], v[74:75], v[164:165]
	v_cvt_pk_bf16_f32 v164, v162, v163
	v_cvt_pk_bf16_f32 v165, v166, v167

; #define LAS __attribute__((address_space(3)))
; __device__ __forceinline__ u32x2 pack4(f32x4 v) { u32x2 r; r.x = cvt_pk(v[0], v[1]); r.y = cvt_pk(v[2], v[3]); return r; }
; __device__ __forceinline__ float dpp_shr1(float v) { return __builtin_bit_cast(float, __builtin_amdgcn_update_dpp(0, __builtin_bit_cast(int, v), 0x111, 0xf, 0xf, true)); }
; __device__ __forceinline__ float dpp_shr2(float v) { return __builtin_bit_cast(float, __builtin_amdgcn_update_dpp(0, __builtin_bit_cast(int, v), 0x112, 0xf, 0xf, true)); }
; #define FOR_AI_M _Pragma("unroll") for (int ai = 0; ai < 2; ++ai) _Pragma("unroll") for (int m = 0; m < 4; ++m)
;     __device__ __forceinline__ void operator()(EPI_ARGS) const {
;     ...
;         FOR_AI_M {
;             const int R = ai * 128 + wr * 64 + m * 16 + fr; const int rb = ai * 8 + wr * 4 + m;
;             u32x4 ow;
;             const bool valid = gather ? ((R & 3) >= 2) : (R >= 2);
;             const int orow = gather ? (256 * (R >> 2) + 252 + (R & 3)) : (256 * u.pm + R - 2);
; #pragma unroll
;             for (int n = 0; n < 2; ++n) {
;                 const int cl = wc * 32 + 8 * fq + 4 * n;
;                 f32x4 hA = (f32x4){0.f, 0.f, 0.f, 0.f}, hB = (f32x4){0.f, 0.f, 0.f, 0.f};
;                 if (fr < 2 && rb > 0) { hA = *(const LAS f32x4*)(halo + (((rb - 1) * 2 + fr) * 128 + cl)); if (fr == 0) hB = *(const LAS f32x4*)(halo + (((rb - 1) * 2 + 1) * 128 + cl)); }
;                 const f32x4 g0 = acc[ai][0][m][n], vv = acc[ai][1][m][n];
;                 f32x4 d1, d2;
; #pragma unroll
;                 for (int e = 0; e < 4; ++e) { d1[e] = dpp_shr1(g0[e]); d2[e] = dpp_shr2(g0[e]); }
;                 const f32x4 g1 = d1 + hB, g2 = d2 + hA;
;                 const f32x4 cv = W0[n] * g2 + (W1[n] * g1 + (W2[n] * g0 + BB[n]));
;                 const f32x4 tt = cv * -1.4426950408889634f; f32x4 den;
; #pragma unroll
;                 for (int e = 0; e < 4; ++e) den[e] = __builtin_amdgcn_exp2f(tt[e]);
;                 den = den + 1.0f; f32x4 rc;
; #pragma unroll
;                 for (int e = 0; e < 4; ++e) rc[e] = __builtin_amdgcn_rcpf(den[e]);
;                 const f32x4 o = (cv * rc) * vv;
;                 const u32x2 pk = pack4(o); if (n == 0) { ow.x = pk.x; ow.y = pk.y; } else { ow.z = pk.x; ow.w = pk.y; }
;             }
;             if (valid) *(u32x4*)(ACT + ((size_t)orow * DFF + u.pn * 128 + wc * 32 + 8 * fq)) = ow;
.LBB0_1161:
	s_waitcnt lgkmcnt(0)
	v_mov_b32_dpp v168, v62 row_ror:1 row_mask:0xf bank_mask:0xf
	v_mov_b32_dpp v169, v63 row_ror:1 row_mask:0xf bank_mask:0xf
	s_nop 0
	v_mov_b32_dpp v168, v54 row_shr:1 row_mask:0xf bank_mask:0xf
	v_mov_b32_dpp v169, v55 row_shr:1 row_mask:0xf bank_mask:0xf
	v_mov_b32_dpp v166, v60 row_ror:1 row_mask:0xf bank_mask:0xf
	v_mov_b32_dpp v167, v61 row_ror:1 row_mask:0xf bank_mask:0xf
	s_nop 0
	v_mov_b32_dpp v166, v52 row_shr:1 row_mask:0xf bank_mask:0xf
	v_mov_b32_dpp v167, v53 row_shr:1 row_mask:0xf bank_mask:0xf
	v_mov_b32_dpp v162, v60 row_ror:2 row_mask:0xf bank_mask:0xf
	v_mov_b32_dpp v163, v61 row_ror:2 row_mask:0xf bank_mask:0xf
	s_nop 0
	v_mov_b32_dpp v162, v52 row_shr:2 row_mask:0xf bank_mask:0xf
	v_mov_b32_dpp v163, v53 row_shr:2 row_mask:0xf bank_mask:0xf
	v_pk_fma_f32 v[200:201], v[154:155], v[54:55], v[158:159]
	v_pk_fma_f32 v[202:203], v[152:153], v[52:53], v[156:157]
	v_mov_b32_dpp v164, v62 row_ror:2 row_mask:0xf bank_mask:0xf
	v_mov_b32_dpp v165, v63 row_ror:2 row_mask:0xf bank_mask:0xf
	s_nop 0
	v_mov_b32_dpp v164, v54 row_shr:2 row_mask:0xf bank_mask:0xf
	v_mov_b32_dpp v165, v55 row_shr:2 row_mask:0xf bank_mask:0xf
	v_pk_fma_f32 v[166:167], v[148:149], v[166:167], v[202:203]
	v_pk_fma_f32 v[168:169], v[150:151], v[168:169], v[200:201]
	v_pk_fma_f32 v[162:163], v[144:145], v[162:163], v[166:167]
	v_pk_fma_f32 v[164:165], v[146:147], v[164:165], v[168:169]
	v_mul_f32_e32 v161, 0xbfb8aa3b, v162
	v_mul_f32_e32 v167, 0xbfb8aa3b, v164
	v_exp_f32_e32 v166, v161
	v_mul_f32_e32 v161, 0xbfb8aa3b, v163
	v_exp_f32_e32 v168, v167
	v_mul_f32_e32 v167, 0xbfb8aa3b, v165
	v_exp_f32_e32 v169, v167
	v_exp_f32_e32 v167, v161
	v_mov_b32_e32 v199, v198
	v_mov_b32_e32 v200, v198
	v_pk_add_f32 v[168:169], v[168:169], 1.0 op_sel_hi:[1,0]
	v_pk_add_f32 v[166:167], v[166:167], 1.0 op_sel_hi:[1,0]
	v_rcp_f32_e32 v168, v168
	v_rcp_f32_e32 v166, v166
	v_rcp_f32_e32 v167, v167
	v_rcp_f32_e32 v169, v169
	v_mov_b32_e32 v201, v198
	v_pk_mul_f32 v[22:23], v[22:23], v[200:201]
	v_pk_mul_f32 v[20:21], v[20:21], v[198:199]
	v_pk_mul_f32 v[162:163], v[162:163], v[166:167]
	v_pk_mul_f32 v[164:165], v[164:165], v[168:169]
	v_pk_mul_f32 v[162:163], v[20:21], v[162:163]
	v_pk_mul_f32 v[166:167], v[22:23], v[164:165]
	v_cvt_pk_bf16_f32 v164, v162, v163
	v_cvt_pk_bf16_f32 v165, v166, v167

; #define LAS __attribute__((address_space(3)))
; __device__ __forceinline__ u32x2 pack4(f32x4 v) { u32x2 r; r.x = cvt_pk(v[0], v[1]); r.y = cvt_pk(v[2], v[3]); return r; }
; __device__ __forceinline__ float dpp_shr1(float v) { return __builtin_bit_cast(float, __builtin_amdgcn_update_dpp(0, __builtin_bit_cast(int, v), 0x111, 0xf, 0xf, true)); }
; __device__ __forceinline__ float dpp_shr2(float v) { return __builtin_bit_cast(float, __builtin_amdgcn_update_dpp(0, __builtin_bit_cast(int, v), 0x112, 0xf, 0xf, true)); }
; #define FOR_AI_M _Pragma("unroll") for (int ai = 0; ai < 2; ++ai) _Pragma("unroll") for (int m = 0; m < 4; ++m)
;     __device__ __forceinline__ void operator()(EPI_ARGS) const {
;     ...
;         FOR_AI_M {
;             const int R = ai * 128 + wr * 64 + m * 16 + fr; const int rb = ai * 8 + wr * 4 + m;
;             u32x4 ow;
;             const bool valid = gather ? ((R & 3) >= 2) : (R >= 2);
;             const int orow = gather ? (256 * (R >> 2) + 252 + (R & 3)) : (256 * u.pm + R - 2);
; #pragma unroll
;             for (int n = 0; n < 2; ++n) {
;                 const int cl = wc * 32 + 8 * fq + 4 * n;
;                 f32x4 hA = (f32x4){0.f, 0.f, 0.f, 0.f}, hB = (f32x4){0.f, 0.f, 0.f, 0.f};
;                 if (fr < 2 && rb > 0) { hA = *(const LAS f32x4*)(halo + (((rb - 1) * 2 + fr) * 128 + cl)); if (fr == 0) hB = *(const LAS f32x4*)(halo + (((rb - 1) * 2 + 1) * 128 + cl)); }
;                 const f32x4 g0 = acc[ai][0][m][n], vv = acc[ai][1][m][n];
;                 f32x4 d1, d2;
; #pragma unroll
;                 for (int e = 0; e < 4; ++e) { d1[e] = dpp_shr1(g0[e]); d2[e] = dpp_shr2(g0[e]); }
;                 const f32x4 g1 = d1 + hB, g2 = d2 + hA;
;                 const f32x4 cv = W0[n] * g2 + (W1[n] * g1 + (W2[n] * g0 + BB[n]));
;                 const f32x4 tt = cv * -1.4426950408889634f; f32x4 den;
; #pragma unroll
;                 for (int e = 0; e < 4; ++e) den[e] = __builtin_amdgcn_exp2f(tt[e]);
;                 den = den + 1.0f; f32x4 rc;
; #pragma unroll
;                 for (int e = 0; e < 4; ++e) rc[e] = __builtin_amdgcn_rcpf(den[e]);
;                 const f32x4 o = (cv * rc) * vv;
;                 const u32x2 pk = pack4(o); if (n == 0) { ow.x = pk.x; ow.y = pk.y; } else { ow.z = pk.x; ow.w = pk.y; }
;             }
;             if (valid) *(u32x4*)(ACT + ((size_t)orow * DFF + u.pn * 128 + wc * 32 + 8 * fq)) = ow;
.LBB0_1171:
	s_waitcnt lgkmcnt(0)
	v_mov_b32_dpp v168, v54 row_ror:1 row_mask:0xf bank_mask:0xf
	v_mov_b32_dpp v169, v55 row_ror:1 row_mask:0xf bank_mask:0xf
	s_nop 0
	v_mov_b32_dpp v168, v46 row_shr:1 row_mask:0xf bank_mask:0xf
	v_mov_b32_dpp v169, v47 row_shr:1 row_mask:0xf bank_mask:0xf
	v_mov_b32_dpp v166, v52 row_ror:1 row_mask:0xf bank_mask:0xf
	v_mov_b32_dpp v167, v53 row_ror:1 row_mask:0xf bank_mask:0xf
	s_nop 0
	v_mov_b32_dpp v166, v44 row_shr:1 row_mask:0xf bank_mask:0xf
	v_mov_b32_dpp v167, v45 row_shr:1 row_mask:0xf bank_mask:0xf
	v_mov_b32_dpp v162, v52 row_ror:2 row_mask:0xf bank_mask:0xf
	v_mov_b32_dpp v163, v53 row_ror:2 row_mask:0xf bank_mask:0xf
	s_nop 0
	v_mov_b32_dpp v162, v44 row_shr:2 row_mask:0xf bank_mask:0xf
	v_mov_b32_dpp v163, v45 row_shr:2 row_mask:0xf bank_mask:0xf
	v_pk_fma_f32 v[198:199], v[154:155], v[46:47], v[158:159]
	v_pk_fma_f32 v[200:201], v[152:153], v[44:45], v[156:157]
	v_mov_b32_dpp v164, v54 row_ror:2 row_mask:0xf bank_mask:0xf
	v_mov_b32_dpp v165, v55 row_ror:2 row_mask:0xf bank_mask:0xf
	s_nop 0
	v_mov_b32_dpp v164, v46 row_shr:2 row_mask:0xf bank_mask:0xf
	v_mov_b32_dpp v165, v47 row_shr:2 row_mask:0xf bank_mask:0xf
	v_pk_fma_f32 v[166:167], v[148:149], v[166:167], v[200:201]
	v_pk_fma_f32 v[168:169], v[150:151], v[168:169], v[198:199]
	v_pk_fma_f32 v[162:163], v[144:145], v[162:163], v[166:167]
	v_pk_fma_f32 v[164:165], v[146:147], v[164:165], v[168:169]
	v_mul_f32_e32 v161, 0xbfb8aa3b, v162
	v_mul_f32_e32 v167, 0xbfb8aa3b, v164
	v_exp_f32_e32 v166, v161
	v_mul_f32_e32 v161, 0xbfb8aa3b, v163
	v_exp_f32_e32 v168, v167
	v_mul_f32_e32 v167, 0xbfb8aa3b, v165
	v_exp_f32_e32 v169, v167
	v_exp_f32_e32 v167, v161
	v_mov_b32_e32 v197, v196
	v_mov_b32_e32 v198, v196
	v_pk_add_f32 v[168:169], v[168:169], 1.0 op_sel_hi:[1,0]
	v_pk_add_f32 v[166:167], v[166:167], 1.0 op_sel_hi:[1,0]
	v_rcp_f32_e32 v168, v168
	v_rcp_f32_e32 v166, v166
	v_rcp_f32_e32 v167, v167
	v_rcp_f32_e32 v169, v169
	v_mov_b32_e32 v199, v196
	v_pk_mul_f32 v[14:15], v[14:15], v[198:199]
	v_pk_mul_f32 v[12:13], v[12:13], v[196:197]
	v_pk_mul_f32 v[162:163], v[162:163], v[166:167]
	v_pk_mul_f32 v[164:165], v[164:165], v[168:169]
	v_pk_mul_f32 v[162:163], v[12:13], v[162:163]
	v_pk_mul_f32 v[166:167], v[14:15], v[164:165]
	v_cvt_pk_bf16_f32 v164, v162, v163
	v_cvt_pk_bf16_f32 v165, v166, v167

; #define LAS __attribute__((address_space(3)))
; __device__ __forceinline__ u32x2 pack4(f32x4 v) { u32x2 r; r.x = cvt_pk(v[0], v[1]); r.y = cvt_pk(v[2], v[3]); return r; }
; __device__ __forceinline__ float dpp_shr1(float v) { return __builtin_bit_cast(float, __builtin_amdgcn_update_dpp(0, __builtin_bit_cast(int, v), 0x111, 0xf, 0xf, true)); }
; __device__ __forceinline__ float dpp_shr2(float v) { return __builtin_bit_cast(float, __builtin_amdgcn_update_dpp(0, __builtin_bit_cast(int, v), 0x112, 0xf, 0xf, true)); }
; #define FOR_AI_M _Pragma("unroll") for (int ai = 0; ai < 2; ++ai) _Pragma("unroll") for (int m = 0; m < 4; ++m)
;     __device__ __forceinline__ void operator()(EPI_ARGS) const {
;     ...
;         FOR_AI_M {
;             const int R = ai * 128 + wr * 64 + m * 16 + fr; const int rb = ai * 8 + wr * 4 + m;
;             u32x4 ow;
;             const bool valid = gather ? ((R & 3) >= 2) : (R >= 2);
;             const int orow = gather ? (256 * (R >> 2) + 252 + (R & 3)) : (256 * u.pm + R - 2);
; #pragma unroll
;             for (int n = 0; n < 2; ++n) {
;                 const int cl = wc * 32 + 8 * fq + 4 * n;
;                 f32x4 hA = (f32x4){0.f, 0.f, 0.f, 0.f}, hB = (f32x4){0.f, 0.f, 0.f, 0.f};
;                 if (fr < 2 && rb > 0) { hA = *(const LAS f32x4*)(halo + (((rb - 1) * 2 + fr) * 128 + cl)); if (fr == 0) hB = *(const LAS f32x4*)(halo + (((rb - 1) * 2 + 1) * 128 + cl)); }
;                 const f32x4 g0 = acc[ai][0][m][n], vv = acc[ai][1][m][n];
;                 f32x4 d1, d2;
; #pragma unroll
;                 for (int e = 0; e < 4; ++e) { d1[e] = dpp_shr1(g0[e]); d2[e] = dpp_shr2(g0[e]); }
;                 const f32x4 g1 = d1 + hB, g2 = d2 + hA;
;                 const f32x4 cv = W0[n] * g2 + (W1[n] * g1 + (W2[n] * g0 + BB[n]));
;                 const f32x4 tt = cv * -1.4426950408889634f; f32x4 den;
; #pragma unroll
;                 for (int e = 0; e < 4; ++e) den[e] = __builtin_amdgcn_exp2f(tt[e]);
;                 den = den + 1.0f; f32x4 rc;
; #pragma unroll
;                 for (int e = 0; e < 4; ++e) rc[e] = __builtin_amdgcn_rcpf(den[e]);
;                 const f32x4 o = (cv * rc) * vv;
;                 const u32x2 pk = pack4(o); if (n == 0) { ow.x = pk.x; ow.y = pk.y; } else { ow.z = pk.x; ow.w = pk.y; }
;             }
;             if (valid) *(u32x4*)(ACT + ((size_t)orow * DFF + u.pn * 128 + wc * 32 + 8 * fq)) = ow;
.LBB0_1177:
	s_or_b64 exec, exec, s[8:9]
	v_mov_b32_e32 v160, 0
.LBB0_1181:
	s_waitcnt lgkmcnt(0)
	v_mov_b32_dpp v168, v46 row_ror:1 row_mask:0xf bank_mask:0xf
	v_mov_b32_dpp v169, v47 row_ror:1 row_mask:0xf bank_mask:0xf
	s_nop 0
	v_mov_b32_dpp v168, v38 row_shr:1 row_mask:0xf bank_mask:0xf
	v_mov_b32_dpp v169, v39 row_shr:1 row_mask:0xf bank_mask:0xf
	v_pk_fma_f32 v[154:155], v[154:155], v[38:39], v[158:159]
	v_mov_b32_dpp v166, v44 row_ror:1 row_mask:0xf bank_mask:0xf
	v_mov_b32_dpp v167, v45 row_ror:1 row_mask:0xf bank_mask:0xf
	s_nop 0
	v_mov_b32_dpp v166, v36 row_shr:1 row_mask:0xf bank_mask:0xf
	v_mov_b32_dpp v167, v37 row_shr:1 row_mask:0xf bank_mask:0xf
	v_mov_b32_dpp v164, v46 row_ror:2 row_mask:0xf bank_mask:0xf
	v_mov_b32_dpp v165, v47 row_ror:2 row_mask:0xf bank_mask:0xf
	s_nop 0
	v_mov_b32_dpp v164, v38 row_shr:2 row_mask:0xf bank_mask:0xf
	v_mov_b32_dpp v165, v39 row_shr:2 row_mask:0xf bank_mask:0xf
	v_pk_fma_f32 v[152:153], v[152:153], v[36:37], v[156:157]
	v_pk_fma_f32 v[150:151], v[150:151], v[168:169], v[154:155]
	v_mov_b32_dpp v162, v44 row_ror:2 row_mask:0xf bank_mask:0xf
	v_mov_b32_dpp v163, v45 row_ror:2 row_mask:0xf bank_mask:0xf
	s_nop 0
	v_mov_b32_dpp v162, v36 row_shr:2 row_mask:0xf bank_mask:0xf
	v_mov_b32_dpp v163, v37 row_shr:2 row_mask:0xf bank_mask:0xf
	v_pk_fma_f32 v[148:149], v[148:149], v[166:167], v[152:153]
	v_pk_fma_f32 v[146:147], v[146:147], v[164:165], v[150:151]
	v_pk_fma_f32 v[144:145], v[144:145], v[162:163], v[148:149]
	v_mul_f32_e32 v150, 0xbfb8aa3b, v146
	v_mul_f32_e32 v148, 0xbfb8aa3b, v144
	v_mul_f32_e32 v149, 0xbfb8aa3b, v145
	v_exp_f32_e32 v152, v150
	v_mul_f32_e32 v150, 0xbfb8aa3b, v147
	v_exp_f32_e32 v148, v148
	v_exp_f32_e32 v153, v150
	v_exp_f32_e32 v149, v149
	v_mov_b32_e32 v195, v194
	v_mov_b32_e32 v150, v194
	v_pk_add_f32 v[152:153], v[152:153], 1.0 op_sel_hi:[1,0]
	v_pk_add_f32 v[148:149], v[148:149], 1.0 op_sel_hi:[1,0]
	v_rcp_f32_e32 v152, v152
	v_rcp_f32_e32 v148, v148
	v_rcp_f32_e32 v149, v149
	v_rcp_f32_e32 v153, v153
	v_mov_b32_e32 v151, v194
	v_pk_mul_f32 v[6:7], v[6:7], v[150:151]
	v_pk_mul_f32 v[4:5], v[4:5], v[194:195]
	v_pk_mul_f32 v[144:145], v[144:145], v[148:149]
	v_pk_mul_f32 v[146:147], v[146:147], v[152:153]
	v_pk_mul_f32 v[144:145], v[4:5], v[144:145]
	v_pk_mul_f32 v[146:147], v[6:7], v[146:147]
	v_cvt_pk_bf16_f32 v144, v144, v145
	v_mov_b32_e32 v161, 0
	v_cvt_pk_bf16_f32 v145, v146, v147
	v_mov_b32_e32 v162, 0
	v_mov_b32_e32 v163, 0
.LBB0_1185:
	v_pk_mul_f32 v[2:3], v[2:3], v[150:151]
	s_waitcnt lgkmcnt(0)
	v_mov_b32_dpp v146, v40 row_ror:1 row_mask:0xf bank_mask:0xf
	v_mov_b32_dpp v147, v41 row_ror:1 row_mask:0xf bank_mask:0xf
	s_nop 0
	v_mov_b32_dpp v146, v32 row_shr:1 row_mask:0xf bank_mask:0xf
	v_mov_b32_dpp v147, v33 row_shr:1 row_mask:0xf bank_mask:0xf
	v_pk_fma_f32 v[136:137], v[136:137], v[32:33], v[140:141]
	v_mov_b32_dpp v150, v40 row_ror:2 row_mask:0xf bank_mask:0xf
	v_mov_b32_dpp v151, v41 row_ror:2 row_mask:0xf bank_mask:0xf
	s_nop 0
	v_mov_b32_dpp v150, v32 row_shr:2 row_mask:0xf bank_mask:0xf
	v_mov_b32_dpp v151, v33 row_shr:2 row_mask:0xf bank_mask:0xf
	v_pk_fma_f32 v[132:133], v[132:133], v[146:147], v[136:137]
	v_pk_fma_f32 v[128:129], v[128:129], v[150:151], v[132:133]
	v_mul_f32_e32 v132, 0xbfb8aa3b, v128
	v_mul_f32_e32 v133, 0xbfb8aa3b, v129
	v_exp_f32_e32 v132, v132
	v_exp_f32_e32 v133, v133
	v_mov_b32_dpp v148, v42 row_ror:1 row_mask:0xf bank_mask:0xf
	v_mov_b32_dpp v149, v43 row_ror:1 row_mask:0xf bank_mask:0xf
	s_nop 0
	v_mov_b32_dpp v148, v34 row_shr:1 row_mask:0xf bank_mask:0xf
	v_mov_b32_dpp v149, v35 row_shr:1 row_mask:0xf bank_mask:0xf
	v_pk_fma_f32 v[138:139], v[138:139], v[34:35], v[142:143]
	v_mov_b32_dpp v154, v42 row_ror:2 row_mask:0xf bank_mask:0xf
	v_mov_b32_dpp v155, v43 row_ror:2 row_mask:0xf bank_mask:0xf
	s_nop 0
	v_mov_b32_dpp v154, v34 row_shr:2 row_mask:0xf bank_mask:0xf
	v_mov_b32_dpp v155, v35 row_shr:2 row_mask:0xf bank_mask:0xf
	v_pk_fma_f32 v[134:135], v[134:135], v[148:149], v[138:139]
	v_pk_add_f32 v[132:133], v[132:133], 1.0 op_sel_hi:[1,0]
	v_pk_fma_f32 v[130:131], v[130:131], v[154:155], v[134:135]
	v_rcp_f32_e32 v132, v132
	v_mul_f32_e32 v134, 0xbfb8aa3b, v130
	v_mul_f32_e32 v135, 0xbfb8aa3b, v131
	v_exp_f32_e32 v134, v134
	v_exp_f32_e32 v135, v135
	v_rcp_f32_e32 v133, v133
	v_add_u32_e32 v152, 0xb0, v222
	v_pk_mul_f32 v[0:1], v[0:1], v[194:195]
	v_pk_add_f32 v[134:135], v[134:135], 1.0 op_sel_hi:[1,0]
	v_pk_mul_f32 v[128:129], v[128:129], v[132:133]
	v_cmp_lt_i32_e32 vcc, 1, v152
	v_rcp_f32_e32 v134, v134
	v_rcp_f32_e32 v135, v135
	v_pk_mul_f32 v[128:129], v[0:1], v[128:129]
	v_pk_mul_f32 v[130:131], v[130:131], v[134:135]
	v_cvt_pk_bf16_f32 v146, v128, v129
	v_cndmask_b32_e64 v128, 0, 1, vcc
	v_cndmask_b32_e64 v128, v128, v208, s[44:45]
	v_and_b32_e32 v128, 1, v128
	v_cmp_eq_u32_e32 vcc, 1, v128
	v_pk_mul_f32 v[130:131], v[2:3], v[130:131]
	s_nop 0
	v_cvt_pk_bf16_f32 v147, v130, v131
	s_and_saveexec_b64 s[8:9], vcc
	s_cbranch_execz .LBB0_1187
	v_lshlrev_b32_e32 v128, 6, v152
	v_add_u32_e32 v129, s29, v152
	v_or3_b32 v128, v128, v191, s74
	v_cndmask_b32_e64 v130, v129, v128, s[44:45]
	v_mov_b64_e32 v[128:129], s[0:1]
	v_mad_i64_i32 v[128:129], s[12:13], v130, s75, v[128:129]
	v_lshl_add_u64 v[128:129], s[10:11], 1, v[128:129]
	v_lshl_add_u64 v[128:129], s[6:7], 1, v[128:129]
	v_lshl_add_u64 v[128:129], v[192:193], 1, v[128:129]
	global_store_dwordx4 v[128:129], v[144:147], off
